# v31 + prologue order mixed per wave: odd waves convert x first and weights second, even waves the reverse, so the two access patterns overlap in time
# speedup vs baseline: 1.0013x; 1.0013x over previous
; #define LAS __attribute__((address_space(3)))
; __device__ __forceinline__ void prologue(const Args& a, LAS unsigned char* lds, int wave, int lane) {
;     unsigned char* ws = a.ws;
;     LAS float* scr = (LAS float*)(lds + wave * 16384);
;     const int gw = blockIdx.x * NWAVES + wave, NGW = gridDim.x * NWAVES;
;     constexpr int I_W1 = (D / 64) * (NFF / 32), I_W2 = (DFF / 64) * (D / 32), I_WIN = (D / 64) * (NPROJ / 32), I_WOUT = (D / 64) * (D / 32);
;     constexpr int I_L = 2 * I_W1 + 2 * I_W2 + I_WIN + I_WOUT;
;     for (int it = gw; it < DEPTH * I_L; it += NGW) {
;         const int l = it / I_L; int r = it % I_L;
;         unsigned char* wl = ws + WS_W + (size_t)l * W_L;
;         if (r < 2 * I_W1) {
;             const bool second = r >= I_W1; if (second) r -= I_W1;
;             const float* W = a.in[second ? 14 : 2] + (size_t)l * D * NFF; const float* ks = a.in[second ? 13 : 1] + (size_t)l * D;
;             const int nblk = NFF / 32, kb = r / nblk, nb = r % nblk, n0 = 32 * nb;
;             const int dst = n0 < DFF ? (n0 / 128) * 256 + (n0 % 128) : ((n0 - DFF) / 128) * 256 + 128 + ((n0 - DFF) % 128);
;             tr_item(W, D, NFF, ks, (bf16*)(wl + (second ? W3_OFF : W1_OFF)), dst, scr, 64 * kb, n0, lane);
;             continue;
;         }
;         r -= 2 * I_W1;
;         if (r < 2 * I_W2) {
;             const bool second = r >= I_W2; if (second) r -= I_W2;
;             const float* W = a.in[second ? 15 : 3] + (size_t)l * DFF * D;
;             const int nblk = D / 32, kb = r / nblk, nb = r % nblk;
;             tr_item(W, DFF, D, nullptr, (bf16*)(wl + (second ? W4_OFF : W2_OFF)), 32 * nb, scr, 64 * kb, 32 * nb, lane);
;             continue;
;         }
;         r -= 2 * I_W2;
;         if (r < I_WIN) {
;             const float* W = a.in[5] + (size_t)l * D * INCOLS; const float* ks = a.in[4] + (size_t)l * D;
;             const int nblk = NPROJ / 32, kb = r / nblk, nb = r % nblk;
;             tr_item(W, D, INCOLS, ks, (bf16*)(wl + WIN_OFF), 32 * nb, scr, 64 * kb, 32 * nb, lane);
;             continue;
;         }
;         r -= I_WIN;
;         {
;             const float* W = a.in[12] + (size_t)l * D * D;
;             const int nblk = D / 32, kb = r / nblk, nb = r % nblk;
;             tr_item(W, D, D, nullptr, (bf16*)(wl + WOUT_OFF), 32 * nb, scr, 64 * kb, 32 * nb, lane);
;         }
.LBB0_11:
	s_load_dwordx16 s[36:51], s[0:1], 0x0
	s_load_dwordx16 s[12:27], s[0:1], 0x40
	v_readlane_b32 s0, v230, 4
	s_lshr_b32 s97, s0, 6
	s_cmp_lt_i32 s52, 1
	s_cselect_b64 s[0:1], -1, 0
	s_cmp_gt_i32 s53, 0
	s_cselect_b64 s[2:3], -1, 0
	s_and_b64 s[62:63], s[0:1], s[2:3]
	s_andn2_b64 vcc, exec, s[62:63]
	v_and_b32_e32 v200, 63, v201
	s_cbranch_vccnz .LBB0_98
	s_lshl_b32 s0, s10, 3
	s_add_i32 s11, s97, s0
	s_cmpk_gt_i32 s11, 0x50ff
	s_cbranch_scc1 .LBB0_81
	s_mov_b32 s101, 0
	s_bitcmp1_b32 s97, 0
	s_cbranch_scc0 .Lw_entry
	s_mov_b32 s101, 1
	s_branch .Lxn_entry
.Lw_entry:
	s_waitcnt lgkmcnt(0)
	v_lshrrev_b32_e32 v1, 3, v200
	v_and_b32_e32 v3, 7, v200
	v_lshlrev_b32_e32 v2, 4, v3
	v_lshlrev_b32_e32 v4, 5, v3
	s_lshl_b32 s0, s97, 14
	v_mul_u32_u24_e32 v6, 0x84, v1
	v_add3_u32 v6, v6, v2, s0
	v_add_u32_e32 v7, 0x420, v6
	v_add_u32_e32 v8, 0x420, v7
	v_add_u32_e32 v9, 0x420, v8
	v_add_u32_e32 v10, 0x420, v9
	v_add_u32_e32 v11, 0x420, v10
	v_add_u32_e32 v12, 0x420, v11
	v_add_u32_e32 v13, 0x420, v12
	v_mul_u32_u24_e32 v5, 0x420, v3
	v_lshl_add_u32 v5, v1, 2, v5
	v_add_u32_e32 v5, s0, v5
	v_lshlrev_b32_e32 v3, 2, v3
	s_mov_b32 s83, s11
	s_cmp_ge_u32 s83, 0x2880
	s_cselect_b32 s0, 1, 0
	s_mul_i32 s1, s0, 0x2880
	s_sub_u32 s1, s83, s1
	s_mul_i32 s2, s0, 0x2880000
	s_add_u32 s68, s34, s2
	s_addc_u32 s69, s35, 0
	s_add_u32 s68, s68, 0x800000
	s_addc_u32 s69, s69, 0
	s_mov_b32 s31, 64
	s_cmp_lt_u32 s1, 0x1600
	s_cbranch_scc1 .Lwq_t0_0
	s_cmp_lt_u32 s1, 0x2100
	s_cbranch_scc1 .Lwq_t1_0
	s_cmp_lt_u32 s1, 0x2680
	s_cbranch_scc1 .Lwq_t2_0
	s_sub_u32 s1, s1, 0x2680
	s_lshr_b32 s3, s1, 5
	s_and_b32 s4, s1, 31
	s_lshl_b32 s5, s0, 22
	s_lshl_b32 s86, s3, 18
	s_add_u32 s5, s5, s86
	s_lshl_b32 s86, s4, 7
	s_add_u32 s5, s5, s86
	s_add_u32 s64, s20, s5
	s_addc_u32 s65, s21, 0
	s_mov_b32 s29, 0x1000
	s_mov_b32 s66, s38
	s_mov_b32 s67, s39
	s_mov_b32 s71, 0
	s_lshl_b32 s5, s4, 16
	s_lshl_b32 s86, s3, 7
	s_add_u32 s5, s5, s86
	s_add_u32 s5, s5, 0x1600000
	s_add_u32 s68, s68, s5
	s_addc_u32 s69, s69, 0
	s_mov_b32 s70, 0x800
	s_branch .Lwq_te_0

; __device__ __forceinline__ void prologue(const Args& a, LAS unsigned char* lds, int wave, int lane) {
;     ...
;     { const float* x = a.in[0]; bf16* XN = (bf16*)(ws + WS_XN); u64* rs0 = (u64*)(ws + WS_ROWSS);
;       for (int m = 2 * gw; m < M; m += 2 * NGW) {
;           const f32x4* xr = (const f32x4*)(x + (size_t)m * D) + lane; f32x4 v[2][4]; float s[2] = {0.f, 0.f};
; #pragma unroll
;           for (int r = 0; r < 2; ++r)
; #pragma unroll
;               for (int j = 0; j < 4; ++j) v[r][j] = xr[r * (D / 4) + 64 * j];
.LBB0_89:
	s_or_b64 exec, exec, s[0:1]
	s_cmp_gt_i32 s11, 0x7fff
	s_cbranch_scc1 .LBB0_98
	s_cmp_eq_u32 s101, 2
	s_cbranch_scc1 .LBB0_98
.Lxn_entry:
	v_mov_b32_e32 v1, 0
	v_lshlrev_b32_e32 v2, 4, v200
	v_lshlrev_b32_e32 v3, 3, v200
	s_add_u32 s66, s34, 0x6000000
	s_addc_u32 s67, s35, 0
	s_add_u32 s68, s34, 0x100000
	s_addc_u32 s69, s35, 0
	s_lshl_b32 s1, s28, 3
	s_mov_b32 s0, s11
	s_waitcnt lgkmcnt(0)
	s_lshl_b32 s2, s0, 12
	s_add_u32 s2, s36, s2
	s_addc_u32 s3, s37, 0
	global_load_dwordx4 v[8:11], v2, s[2:3] offset:0 nt
	global_load_dwordx4 v[12:15], v2, s[2:3] offset:1024 nt
	global_load_dwordx4 v[16:19], v2, s[2:3] offset:2048 nt
	global_load_dwordx4 v[20:23], v2, s[2:3] offset:3072 nt
	s_add_u32 s70, s0, s1
	s_cmp_lt_u32 s70, 0x8000
	s_cbranch_scc0 .Lxn_a
	s_lshl_b32 s2, s70, 12
	s_add_u32 s2, s36, s2
	s_addc_u32 s3, s37, 0
	global_load_dwordx4 v[24:27], v2, s[2:3] offset:0 nt
	global_load_dwordx4 v[28:31], v2, s[2:3] offset:1024 nt
	global_load_dwordx4 v[32:35], v2, s[2:3] offset:2048 nt
	global_load_dwordx4 v[36:39], v2, s[2:3] offset:3072 nt
.Lxn_a:
	s_lshl_b32 s70, s1, 1
	s_add_u32 s70, s0, s70
	s_cmp_lt_u32 s70, 0x8000
	s_cbranch_scc0 .Lxn_a_t
	s_lshl_b32 s2, s70, 12
	s_add_u32 s2, s36, s2
	s_addc_u32 s3, s37, 0
	global_load_dwordx4 v[40:43], v2, s[2:3] offset:0 nt
	global_load_dwordx4 v[44:47], v2, s[2:3] offset:1024 nt
	global_load_dwordx4 v[48:51], v2, s[2:3] offset:2048 nt
	global_load_dwordx4 v[52:55], v2, s[2:3] offset:3072 nt
	s_waitcnt vmcnt(8)
	s_branch .Lxn_a_p

; __device__ __forceinline__ u64 ss_fix(float s) { return (u64)(s * 1099511627776.0f); }
; __device__ __forceinline__ unsigned pk2(float lo, float hi) { return f2bf(lo) | (f2bf(hi) << 16); }
; __device__ __forceinline__ void prologue(const Args& a, LAS unsigned char* lds, int wave, int lane) {
;     ...
;           const f32x4* xr = (const f32x4*)(x + (size_t)m * D) + lane; f32x4 v[2][4]; float s[2] = {0.f, 0.f};
; #pragma unroll
;           for (int r = 0; r < 2; ++r)
; #pragma unroll
;               for (int j = 0; j < 4; ++j) v[r][j] = xr[r * (D / 4) + 64 * j];
; #pragma unroll
;           for (int r = 0; r < 2; ++r) {
; #pragma unroll
;               for (int j = 0; j < 4; ++j) s[r] += (v[r][j][0] * v[r][j][0] + v[r][j][1] * v[r][j][1]) + (v[r][j][2] * v[r][j][2] + v[r][j][3] * v[r][j][3]);
;               s[r] = wave_sum(s[r]); if (lane == 0) rs0[m + r] = ss_fix(s[r]);
;               u32x2* o = (u32x2*)(XN + (size_t)(m + r) * D) + lane;
; #pragma unroll
;               for (int j = 0; j < 4; ++j) { u32x2 w; w.x = pk2(v[r][j][0], v[r][j][1]); w.y = pk2(v[r][j][2], v[r][j][3]); o[64 * j] = w; }
.Lxn_a_p:
	s_lshl_b32 s4, s0, 11
	s_add_u32 s4, s66, s4
	s_addc_u32 s5, s67, 0
	s_lshl_b32 s64, s0, 3
	s_add_u32 s64, s68, s64
	s_addc_u32 s65, s69, 0
	v_mul_f32_e32 v60, v8, v8
	v_fmac_f32_e32 v60, v9, v9
	v_mul_f32_e32 v61, v10, v10
	v_fmac_f32_e32 v61, v11, v11
	v_add_f32_e32 v60, v60, v61
	v_mov_b32_e32 v62, v60
	v_mul_f32_e32 v60, v12, v12
	v_fmac_f32_e32 v60, v13, v13
	v_mul_f32_e32 v61, v14, v14
	v_fmac_f32_e32 v61, v15, v15
	v_add_f32_e32 v60, v60, v61
	v_add_f32_e32 v62, v62, v60
	v_mul_f32_e32 v60, v16, v16
	v_fmac_f32_e32 v60, v17, v17
	v_mul_f32_e32 v61, v18, v18
	v_fmac_f32_e32 v61, v19, v19
	v_add_f32_e32 v60, v60, v61
	v_add_f32_e32 v62, v62, v60
	v_mul_f32_e32 v60, v20, v20
	v_fmac_f32_e32 v60, v21, v21
	v_mul_f32_e32 v61, v22, v22
	v_fmac_f32_e32 v61, v23, v23
	v_add_f32_e32 v60, v60, v61
	v_add_f32_e32 v62, v62, v60
	s_nop 1
	v_add_f32_dpp v62, v62, v62 quad_perm:[1,0,3,2] row_mask:0xf bank_mask:0xf
	s_nop 1
	v_add_f32_dpp v62, v62, v62 quad_perm:[2,3,0,1] row_mask:0xf bank_mask:0xf
	s_nop 1
	v_add_f32_dpp v62, v62, v62 row_half_mirror row_mask:0xf bank_mask:0xf
	s_nop 1
	v_add_f32_dpp v62, v62, v62 row_mirror row_mask:0xf bank_mask:0xf
	s_nop 1
	v_readlane_b32 s72, v62, 0
	v_readlane_b32 s73, v62, 16
	v_readlane_b32 s74, v62, 32
	v_readlane_b32 s75, v62, 48
	s_nop 2
	v_mov_b32_e32 v63, s72
	v_add_f32_e32 v63, s73, v63
	v_add_f32_e32 v63, s74, v63
	v_add_f32_e32 v63, s75, v63
	v_mul_f32_e32 v64, 0x53800000, v63
	v_trunc_f32_e32 v64, v64
	v_mul_f32_e32 v65, 0x2f800000, v64
	v_floor_f32_e32 v65, v65
	v_fmac_f32_e32 v64, 0xcf800000, v65
	v_cvt_u32_f32_e32 v64, v64
	v_cvt_u32_f32_e32 v65, v65
	s_mov_b64 exec, 1
	global_store_dwordx2 v1, v[64:65], s[64:65] sc0 sc1
	s_mov_b64 exec, -1
	v_cvt_pk_bf16_f32 v66, v8, v9
	v_cvt_pk_bf16_f32 v67, v10, v11
	global_store_dwordx2 v3, v[66:67], s[4:5] offset:0 sc0 sc1
	v_cvt_pk_bf16_f32 v68, v12, v13
	v_cvt_pk_bf16_f32 v69, v14, v15
	global_store_dwordx2 v3, v[68:69], s[4:5] offset:512 sc0 sc1
	v_cvt_pk_bf16_f32 v70, v16, v17
	v_cvt_pk_bf16_f32 v71, v18, v19
	global_store_dwordx2 v3, v[70:71], s[4:5] offset:1024 sc0 sc1
	v_cvt_pk_bf16_f32 v72, v20, v21
	v_cvt_pk_bf16_f32 v73, v22, v23
	global_store_dwordx2 v3, v[72:73], s[4:5] offset:1536 sc0 sc1
	s_add_u32 s0, s0, s1
	s_cmp_lt_u32 s0, 0x8000
	s_cbranch_scc0 .Lxn_exit
.Lxn_b:
	s_lshl_b32 s70, s1, 1
	s_add_u32 s70, s0, s70
	s_cmp_lt_u32 s70, 0x8000
	s_cbranch_scc0 .Lxn_b_t
	s_lshl_b32 s2, s70, 12
	s_add_u32 s2, s36, s2
	s_addc_u32 s3, s37, 0
	global_load_dwordx4 v[8:11], v2, s[2:3] offset:0 nt
	global_load_dwordx4 v[12:15], v2, s[2:3] offset:1024 nt
	global_load_dwordx4 v[16:19], v2, s[2:3] offset:2048 nt
	global_load_dwordx4 v[20:23], v2, s[2:3] offset:3072 nt
	s_waitcnt vmcnt(13)
	s_branch .Lxn_b_p

; __device__ __forceinline__ u64 ss_fix(float s) { return (u64)(s * 1099511627776.0f); }
; __device__ __forceinline__ unsigned pk2(float lo, float hi) { return f2bf(lo) | (f2bf(hi) << 16); }
; __device__ __forceinline__ void prologue(const Args& a, LAS unsigned char* lds, int wave, int lane) {
;     ...
;           const f32x4* xr = (const f32x4*)(x + (size_t)m * D) + lane; f32x4 v[2][4]; float s[2] = {0.f, 0.f};
; #pragma unroll
;           for (int r = 0; r < 2; ++r)
; #pragma unroll
;               for (int j = 0; j < 4; ++j) v[r][j] = xr[r * (D / 4) + 64 * j];
; #pragma unroll
;           for (int r = 0; r < 2; ++r) {
; #pragma unroll
;               for (int j = 0; j < 4; ++j) s[r] += (v[r][j][0] * v[r][j][0] + v[r][j][1] * v[r][j][1]) + (v[r][j][2] * v[r][j][2] + v[r][j][3] * v[r][j][3]);
;               s[r] = wave_sum(s[r]); if (lane == 0) rs0[m + r] = ss_fix(s[r]);
;               u32x2* o = (u32x2*)(XN + (size_t)(m + r) * D) + lane;
; #pragma unroll
;               for (int j = 0; j < 4; ++j) { u32x2 w; w.x = pk2(v[r][j][0], v[r][j][1]); w.y = pk2(v[r][j][2], v[r][j][3]); o[64 * j] = w; }
.Lxn_b_p:
	s_lshl_b32 s4, s0, 11
	s_add_u32 s4, s66, s4
	s_addc_u32 s5, s67, 0
	s_lshl_b32 s64, s0, 3
	s_add_u32 s64, s68, s64
	s_addc_u32 s65, s69, 0
	v_mul_f32_e32 v60, v24, v24
	v_fmac_f32_e32 v60, v25, v25
	v_mul_f32_e32 v61, v26, v26
	v_fmac_f32_e32 v61, v27, v27
	v_add_f32_e32 v60, v60, v61
	v_mov_b32_e32 v62, v60
	v_mul_f32_e32 v60, v28, v28
	v_fmac_f32_e32 v60, v29, v29
	v_mul_f32_e32 v61, v30, v30
	v_fmac_f32_e32 v61, v31, v31
	v_add_f32_e32 v60, v60, v61
	v_add_f32_e32 v62, v62, v60
	v_mul_f32_e32 v60, v32, v32
	v_fmac_f32_e32 v60, v33, v33
	v_mul_f32_e32 v61, v34, v34
	v_fmac_f32_e32 v61, v35, v35
	v_add_f32_e32 v60, v60, v61
	v_add_f32_e32 v62, v62, v60
	v_mul_f32_e32 v60, v36, v36
	v_fmac_f32_e32 v60, v37, v37
	v_mul_f32_e32 v61, v38, v38
	v_fmac_f32_e32 v61, v39, v39
	v_add_f32_e32 v60, v60, v61
	v_add_f32_e32 v62, v62, v60
	s_nop 1
	v_add_f32_dpp v62, v62, v62 quad_perm:[1,0,3,2] row_mask:0xf bank_mask:0xf
	s_nop 1
	v_add_f32_dpp v62, v62, v62 quad_perm:[2,3,0,1] row_mask:0xf bank_mask:0xf
	s_nop 1
	v_add_f32_dpp v62, v62, v62 row_half_mirror row_mask:0xf bank_mask:0xf
	s_nop 1
	v_add_f32_dpp v62, v62, v62 row_mirror row_mask:0xf bank_mask:0xf
	s_nop 1
	v_readlane_b32 s72, v62, 0
	v_readlane_b32 s73, v62, 16
	v_readlane_b32 s74, v62, 32
	v_readlane_b32 s75, v62, 48
	s_nop 2
	v_mov_b32_e32 v63, s72
	v_add_f32_e32 v63, s73, v63
	v_add_f32_e32 v63, s74, v63
	v_add_f32_e32 v63, s75, v63
	v_mul_f32_e32 v64, 0x53800000, v63
	v_trunc_f32_e32 v64, v64
	v_mul_f32_e32 v65, 0x2f800000, v64
	v_floor_f32_e32 v65, v65
	v_fmac_f32_e32 v64, 0xcf800000, v65
	v_cvt_u32_f32_e32 v64, v64
	v_cvt_u32_f32_e32 v65, v65
	s_mov_b64 exec, 1
	global_store_dwordx2 v1, v[64:65], s[64:65] sc0 sc1
	s_mov_b64 exec, -1
	v_cvt_pk_bf16_f32 v66, v24, v25
	v_cvt_pk_bf16_f32 v67, v26, v27
	global_store_dwordx2 v3, v[66:67], s[4:5] offset:0 sc0 sc1
	v_cvt_pk_bf16_f32 v68, v28, v29
	v_cvt_pk_bf16_f32 v69, v30, v31
	global_store_dwordx2 v3, v[68:69], s[4:5] offset:512 sc0 sc1
	v_cvt_pk_bf16_f32 v70, v32, v33
	v_cvt_pk_bf16_f32 v71, v34, v35
	global_store_dwordx2 v3, v[70:71], s[4:5] offset:1024 sc0 sc1
	v_cvt_pk_bf16_f32 v72, v36, v37
	v_cvt_pk_bf16_f32 v73, v38, v39
	global_store_dwordx2 v3, v[72:73], s[4:5] offset:1536 sc0 sc1
	s_add_u32 s0, s0, s1
	s_cmp_lt_u32 s0, 0x8000
	s_cbranch_scc0 .Lxn_exit
.Lxn_c:
	s_lshl_b32 s70, s1, 1
	s_add_u32 s70, s0, s70
	s_cmp_lt_u32 s70, 0x8000
	s_cbranch_scc0 .Lxn_c_t
	s_lshl_b32 s2, s70, 12
	s_add_u32 s2, s36, s2
	s_addc_u32 s3, s37, 0
	global_load_dwordx4 v[24:27], v2, s[2:3] offset:0 nt
	global_load_dwordx4 v[28:31], v2, s[2:3] offset:1024 nt
	global_load_dwordx4 v[32:35], v2, s[2:3] offset:2048 nt
	global_load_dwordx4 v[36:39], v2, s[2:3] offset:3072 nt
	s_waitcnt vmcnt(18)
	s_branch .Lxn_c_p

; __device__ __forceinline__ u64 ss_fix(float s) { return (u64)(s * 1099511627776.0f); }
; __device__ __forceinline__ unsigned pk2(float lo, float hi) { return f2bf(lo) | (f2bf(hi) << 16); }
; __device__ __forceinline__ void prologue(const Args& a, LAS unsigned char* lds, int wave, int lane) {
;     ...
;           const f32x4* xr = (const f32x4*)(x + (size_t)m * D) + lane; f32x4 v[2][4]; float s[2] = {0.f, 0.f};
; #pragma unroll
;           for (int r = 0; r < 2; ++r)
; #pragma unroll
;               for (int j = 0; j < 4; ++j) v[r][j] = xr[r * (D / 4) + 64 * j];
; #pragma unroll
;           for (int r = 0; r < 2; ++r) {
; #pragma unroll
;               for (int j = 0; j < 4; ++j) s[r] += (v[r][j][0] * v[r][j][0] + v[r][j][1] * v[r][j][1]) + (v[r][j][2] * v[r][j][2] + v[r][j][3] * v[r][j][3]);
;               s[r] = wave_sum(s[r]); if (lane == 0) rs0[m + r] = ss_fix(s[r]);
;               u32x2* o = (u32x2*)(XN + (size_t)(m + r) * D) + lane;
; #pragma unroll
;               for (int j = 0; j < 4; ++j) { u32x2 w; w.x = pk2(v[r][j][0], v[r][j][1]); w.y = pk2(v[r][j][2], v[r][j][3]); o[64 * j] = w; }
.Lxn_c_p:
	s_lshl_b32 s4, s0, 11
	s_add_u32 s4, s66, s4
	s_addc_u32 s5, s67, 0
	s_lshl_b32 s64, s0, 3
	s_add_u32 s64, s68, s64
	s_addc_u32 s65, s69, 0
	v_mul_f32_e32 v60, v40, v40
	v_fmac_f32_e32 v60, v41, v41
	v_mul_f32_e32 v61, v42, v42
	v_fmac_f32_e32 v61, v43, v43
	v_add_f32_e32 v60, v60, v61
	v_mov_b32_e32 v62, v60
	v_mul_f32_e32 v60, v44, v44
	v_fmac_f32_e32 v60, v45, v45
	v_mul_f32_e32 v61, v46, v46
	v_fmac_f32_e32 v61, v47, v47
	v_add_f32_e32 v60, v60, v61
	v_add_f32_e32 v62, v62, v60
	v_mul_f32_e32 v60, v48, v48
	v_fmac_f32_e32 v60, v49, v49
	v_mul_f32_e32 v61, v50, v50
	v_fmac_f32_e32 v61, v51, v51
	v_add_f32_e32 v60, v60, v61
	v_add_f32_e32 v62, v62, v60
	v_mul_f32_e32 v60, v52, v52
	v_fmac_f32_e32 v60, v53, v53
	v_mul_f32_e32 v61, v54, v54
	v_fmac_f32_e32 v61, v55, v55
	v_add_f32_e32 v60, v60, v61
	v_add_f32_e32 v62, v62, v60
	s_nop 1
	v_add_f32_dpp v62, v62, v62 quad_perm:[1,0,3,2] row_mask:0xf bank_mask:0xf
	s_nop 1
	v_add_f32_dpp v62, v62, v62 quad_perm:[2,3,0,1] row_mask:0xf bank_mask:0xf
	s_nop 1
	v_add_f32_dpp v62, v62, v62 row_half_mirror row_mask:0xf bank_mask:0xf
	s_nop 1
	v_add_f32_dpp v62, v62, v62 row_mirror row_mask:0xf bank_mask:0xf
	s_nop 1
	v_readlane_b32 s72, v62, 0
	v_readlane_b32 s73, v62, 16
	v_readlane_b32 s74, v62, 32
	v_readlane_b32 s75, v62, 48
	s_nop 2
	v_mov_b32_e32 v63, s72
	v_add_f32_e32 v63, s73, v63
	v_add_f32_e32 v63, s74, v63
	v_add_f32_e32 v63, s75, v63
	v_mul_f32_e32 v64, 0x53800000, v63
	v_trunc_f32_e32 v64, v64
	v_mul_f32_e32 v65, 0x2f800000, v64
	v_floor_f32_e32 v65, v65
	v_fmac_f32_e32 v64, 0xcf800000, v65
	v_cvt_u32_f32_e32 v64, v64
	v_cvt_u32_f32_e32 v65, v65
	s_mov_b64 exec, 1
	global_store_dwordx2 v1, v[64:65], s[64:65] sc0 sc1
	s_mov_b64 exec, -1
	v_cvt_pk_bf16_f32 v66, v40, v41
	v_cvt_pk_bf16_f32 v67, v42, v43
	global_store_dwordx2 v3, v[66:67], s[4:5] offset:0 sc0 sc1
	v_cvt_pk_bf16_f32 v68, v44, v45
	v_cvt_pk_bf16_f32 v69, v46, v47
	global_store_dwordx2 v3, v[68:69], s[4:5] offset:512 sc0 sc1
	v_cvt_pk_bf16_f32 v70, v48, v49
	v_cvt_pk_bf16_f32 v71, v50, v51
	global_store_dwordx2 v3, v[70:71], s[4:5] offset:1024 sc0 sc1
	v_cvt_pk_bf16_f32 v72, v52, v53
	v_cvt_pk_bf16_f32 v73, v54, v55
	global_store_dwordx2 v3, v[72:73], s[4:5] offset:1536 sc0 sc1
	s_add_u32 s0, s0, s1
	s_cmp_lt_u32 s0, 0x8000
	s_cbranch_scc0 .Lxn_exit
.Lxn_d:
	s_lshl_b32 s70, s1, 1
	s_add_u32 s70, s0, s70
	s_cmp_lt_u32 s70, 0x8000
	s_cbranch_scc0 .Lxn_d_t
	s_lshl_b32 s2, s70, 12
	s_add_u32 s2, s36, s2
	s_addc_u32 s3, s37, 0
	global_load_dwordx4 v[40:43], v2, s[2:3] offset:0 nt
	global_load_dwordx4 v[44:47], v2, s[2:3] offset:1024 nt
	global_load_dwordx4 v[48:51], v2, s[2:3] offset:2048 nt
	global_load_dwordx4 v[52:55], v2, s[2:3] offset:3072 nt
	s_waitcnt vmcnt(18)
	s_branch .Lxn_d_p

; __device__ __forceinline__ void prologue(const Args& a, LAS unsigned char* lds, int wave, int lane) {
;     ...
;       for (int m = 2 * gw; m < M; m += 2 * NGW) {
;           const f32x4* xr = (const f32x4*)(x + (size_t)m * D) + lane; f32x4 v[2][4]; float s[2] = {0.f, 0.f};
; #pragma unroll
;           for (int r = 0; r < 2; ++r)
; #pragma unroll
;               for (int j = 0; j < 4; ++j) v[r][j] = xr[r * (D / 4) + 64 * j];
.Lxn_e:
	s_lshl_b32 s70, s1, 1
	s_add_u32 s70, s0, s70
	s_cmp_lt_u32 s70, 0x8000
	s_cbranch_scc0 .Lxn_e_t
	s_lshl_b32 s2, s70, 12
	s_add_u32 s2, s36, s2
	s_addc_u32 s3, s37, 0
	global_load_dwordx4 v[8:11], v2, s[2:3] offset:0 nt
	global_load_dwordx4 v[12:15], v2, s[2:3] offset:1024 nt
	global_load_dwordx4 v[16:19], v2, s[2:3] offset:2048 nt
	global_load_dwordx4 v[20:23], v2, s[2:3] offset:3072 nt
	s_waitcnt vmcnt(18)
	s_branch .Lxn_e_p

; __device__ __forceinline__ u64 ss_fix(float s) { return (u64)(s * 1099511627776.0f); }
; __device__ __forceinline__ unsigned pk2(float lo, float hi) { return f2bf(lo) | (f2bf(hi) << 16); }
; __device__ __forceinline__ void prologue(const Args& a, LAS unsigned char* lds, int wave, int lane) {
;     ...
;           const f32x4* xr = (const f32x4*)(x + (size_t)m * D) + lane; f32x4 v[2][4]; float s[2] = {0.f, 0.f};
; #pragma unroll
;           for (int r = 0; r < 2; ++r)
; #pragma unroll
;               for (int j = 0; j < 4; ++j) v[r][j] = xr[r * (D / 4) + 64 * j];
; #pragma unroll
;           for (int r = 0; r < 2; ++r) {
; #pragma unroll
;               for (int j = 0; j < 4; ++j) s[r] += (v[r][j][0] * v[r][j][0] + v[r][j][1] * v[r][j][1]) + (v[r][j][2] * v[r][j][2] + v[r][j][3] * v[r][j][3]);
;               s[r] = wave_sum(s[r]); if (lane == 0) rs0[m + r] = ss_fix(s[r]);
;               u32x2* o = (u32x2*)(XN + (size_t)(m + r) * D) + lane;
; #pragma unroll
;               for (int j = 0; j < 4; ++j) { u32x2 w; w.x = pk2(v[r][j][0], v[r][j][1]); w.y = pk2(v[r][j][2], v[r][j][3]); o[64 * j] = w; }
;           }
;       } }
.Lxn_e_p:
	s_lshl_b32 s4, s0, 11
	s_add_u32 s4, s66, s4
	s_addc_u32 s5, s67, 0
	s_lshl_b32 s64, s0, 3
	s_add_u32 s64, s68, s64
	s_addc_u32 s65, s69, 0
	v_mul_f32_e32 v60, v24, v24
	v_fmac_f32_e32 v60, v25, v25
	v_mul_f32_e32 v61, v26, v26
	v_fmac_f32_e32 v61, v27, v27
	v_add_f32_e32 v60, v60, v61
	v_mov_b32_e32 v62, v60
	v_mul_f32_e32 v60, v28, v28
	v_fmac_f32_e32 v60, v29, v29
	v_mul_f32_e32 v61, v30, v30
	v_fmac_f32_e32 v61, v31, v31
	v_add_f32_e32 v60, v60, v61
	v_add_f32_e32 v62, v62, v60
	v_mul_f32_e32 v60, v32, v32
	v_fmac_f32_e32 v60, v33, v33
	v_mul_f32_e32 v61, v34, v34
	v_fmac_f32_e32 v61, v35, v35
	v_add_f32_e32 v60, v60, v61
	v_add_f32_e32 v62, v62, v60
	v_mul_f32_e32 v60, v36, v36
	v_fmac_f32_e32 v60, v37, v37
	v_mul_f32_e32 v61, v38, v38
	v_fmac_f32_e32 v61, v39, v39
	v_add_f32_e32 v60, v60, v61
	v_add_f32_e32 v62, v62, v60
	s_nop 1
	v_add_f32_dpp v62, v62, v62 quad_perm:[1,0,3,2] row_mask:0xf bank_mask:0xf
	s_nop 1
	v_add_f32_dpp v62, v62, v62 quad_perm:[2,3,0,1] row_mask:0xf bank_mask:0xf
	s_nop 1
	v_add_f32_dpp v62, v62, v62 row_half_mirror row_mask:0xf bank_mask:0xf
	s_nop 1
	v_add_f32_dpp v62, v62, v62 row_mirror row_mask:0xf bank_mask:0xf
	s_nop 1
	v_readlane_b32 s72, v62, 0
	v_readlane_b32 s73, v62, 16
	v_readlane_b32 s74, v62, 32
	v_readlane_b32 s75, v62, 48
	s_nop 2
	v_mov_b32_e32 v63, s72
	v_add_f32_e32 v63, s73, v63
	v_add_f32_e32 v63, s74, v63
	v_add_f32_e32 v63, s75, v63
	v_mul_f32_e32 v64, 0x53800000, v63
	v_trunc_f32_e32 v64, v64
	v_mul_f32_e32 v65, 0x2f800000, v64
	v_floor_f32_e32 v65, v65
	v_fmac_f32_e32 v64, 0xcf800000, v65
	v_cvt_u32_f32_e32 v64, v64
	v_cvt_u32_f32_e32 v65, v65
	s_mov_b64 exec, 1
	global_store_dwordx2 v1, v[64:65], s[64:65] sc0 sc1
	s_mov_b64 exec, -1
	v_cvt_pk_bf16_f32 v66, v24, v25
	v_cvt_pk_bf16_f32 v67, v26, v27
	global_store_dwordx2 v3, v[66:67], s[4:5] offset:0 sc0 sc1
	v_cvt_pk_bf16_f32 v68, v28, v29
	v_cvt_pk_bf16_f32 v69, v30, v31
	global_store_dwordx2 v3, v[68:69], s[4:5] offset:512 sc0 sc1
	v_cvt_pk_bf16_f32 v70, v32, v33
	v_cvt_pk_bf16_f32 v71, v34, v35
	global_store_dwordx2 v3, v[70:71], s[4:5] offset:1024 sc0 sc1
	v_cvt_pk_bf16_f32 v72, v36, v37
	v_cvt_pk_bf16_f32 v73, v38, v39
	global_store_dwordx2 v3, v[72:73], s[4:5] offset:1536 sc0 sc1
	s_add_u32 s0, s0, s1
	s_cmp_lt_u32 s0, 0x8000
	s_cbranch_scc0 .Lxn_exit
	s_branch .Lxn_c
.Lxn_exit:
	s_cmp_eq_u32 s101, 1
	s_cbranch_scc0 .LBB0_98
	s_mov_b32 s101, 2
	s_branch .Lw_entry
